# P0 time-balanced mapping: adaLN-GEMV waves (cols<4096) do only their GEMV item, all weight conversions spread over the other 1536 waves; cols>=4096 GEMV deferred into attention queue
# speedup vs baseline: 1.0334x; 1.0037x over previous
; #define LAS __attribute__((address_space(3)))
; #define IN_cvec PTRF(1)
; #define IN_w_ada PTRF(2)
; __global__ void __launch_bounds__(512, 2) fwd_kernel(Args a) {
;     ...
;     if (IN(0)) for (int rep = 0; rep < REPS(0); ++rep) { DECL_WS();
;         const float* const wada_p = IN_w_ada; const float* const c_p = IN_cvec;
;         LAS float* scr = (LAS float*)(lds + wave * 16640);
;         constexpr int I_ADA = 48 * KC_ADA, I_IN = 32 * 128, I_UP = 32 * 128, I_DN = 128 * 32, I_OUT = 32 * 32, I_BR = 16 * 32, I_Q = 8 * 24, I_KV = 4 * 32;
;         constexpr int NITEMS = I_ADA + I_IN + I_UP + I_DN + I_OUT + 2 * I_BR + I_Q + I_KV;
;         for (int it = gw; it < NITEMS; it += NGW) {
;             int r = it;
;             if (r < I_ADA) {
;                 const int cb = r % 48, kc = r / 48, col = cb * 256 + lane * 4;
.LBB0_21:
	s_lshr_b32 s50, s28, 6
	s_lshl_b32 s0, s93, 3
	s_add_i32 s96, s50, s0
	s_lshl_b32 s14, s92, 3
	s_cmp_lt_i32 s90, 1
	s_cselect_b64 s[0:1], -1, 0
	s_cmp_gt_i32 s91, 0
	s_cselect_b64 s[2:3], -1, 0
	s_and_b64 s[8:9], s[0:1], s[2:3]
	v_writelane_b32 v255, s68, 3
	v_and_b32_e32 v196, 63, v0
	s_andn2_b64 vcc, exec, s[8:9]
	v_lshlrev_b32_e32 v1, 1, v0
	v_writelane_b32 v255, s69, 4
	s_cbranch_vccnz .LBB0_221
	s_mov_b32 s100, 0
	s_mov_b32 s97, s14
	s_cmp_ge_u32 s96, 0x600
	s_cbranch_scc1 .Lp0_hi
	s_mul_i32 s0, s96, 0x556
	s_lshr_b32 s0, s0, 16
	s_mul_i32 s1, s0, 48
	s_sub_i32 s1, s96, s1
	s_cmp_lt_u32 s1, 16
	s_cbranch_scc0 .Lp0_mid
	s_mov_b32 s99, s96
	s_mov_b32 s101, s96
	s_mov_b32 s98, -1
	s_branch .Lp0_entry
.Lp0_mid:
	s_lshl_b32 s0, s0, 5
	s_add_i32 s98, s0, s1
	s_add_i32 s98, s98, 0x1f0
	s_branch .Lp0_conv
.Lp0_hi:
	s_sub_i32 s98, s96, 0x600
.Lp0_conv:
	s_add_i32 s99, s98, 0x600
	s_movk_i32 s101, 0x15ff
	s_movk_i32 s14, 0x600

; #define IN_w_in PTRF(4)
; __global__ void __launch_bounds__(512, 2) fwd_kernel(Args a) {
;     ...
;         for (int it = gw; it < NITEMS; it += NGW) {
;             int r = it;
;             if (r < I_ADA) {
;                 const int cb = r % 48, kc = r / 48, col = cb * 256 + lane * 4;
;                 f32x4 s0 = {0.f, 0.f, 0.f, 0.f}, s1 = {0.f, 0.f, 0.f, 0.f};
;                 const int kbeg = kc * (DMODEL / KC_ADA);
; #pragma unroll 16
;                 for (int k = kbeg; k < kbeg + DMODEL / KC_ADA; ++k) {
;                     const f32x4 wv = __builtin_nontemporal_load((const f32x4*)(wada_p + (size_t)k * NADA + col));
;                     const float c0 = c_p[k], c1 = c_p[DMODEL + k];
;                     const float a0 = c0 * sigmoidf_(c0), a1 = c1 * sigmoidf_(c1);
;                     s0 += wv * a0; s1 += wv * a1;
;                 }
;                 *(f32x4*)(part + (size_t)(kc * 2 + 0) * NADA + col) = s0; *(f32x4*)(part + (size_t)(kc * 2 + 1) * NADA + col) = s1;
;                 continue;
;             }
;             r -= I_ADA;
;             if (r < I_IN) { conv_item(IN_w_in, 2048, DIN, WinT, scr, r / 128, r % 128, lane, nullptr, map_win); continue; } r -= I_IN;
;             if (r < I_UP) { conv_item(IN_w_up, 2048, DFF, WupT, scr, r / 128, r % 128, lane, nullptr, map_id, true); continue; } r -= I_UP;
;             if (r < I_DN) { conv_item(IN_w_dn, 8192, DMODEL, WdnT, scr, r / 32, r % 32, lane, nullptr, map_id, true); continue; } r -= I_DN;
;             if (r < I_OUT) { conv_item(IN_w_out, 2048, DMODEL, WoutT, scr, r / 32, r % 32, lane, nullptr, map_id, true); continue; } r -= I_OUT;
;             if (r < I_BR) { conv_item(IN_w_bf, 1024, DMODEL, WbrT, scr, r / 32, r % 32, lane, nullptr, map_id, true); continue; } r -= I_BR;
;             if (r < I_BR) { conv_item(IN_w_bm, 1024, DMODEL, WbrT + (size_t)2048 * 1024, scr, r / 32, r % 32, lane, nullptr, map_id, true); continue; } r -= I_BR;
;     ...
;         for (int e = bx * 512 + tid; e < SEQ * 32; e += G * 512) {
;             const int pos = e >> 5, i = e & 31;
;             const float inv = powf(10000.0f, -(float)(2 * i) / 64.0f);
;             const float ang = (float)pos * inv;
;             const double ad = (double)ang; const double n = rint(ad * 0.15915494309189535); const float rr = (float)(ad - n * 6.283185307179586);
;             cost[e] = cosf(rr); sint[e] = sinf(rr);
.LBB0_209:
	s_cmp_eq_u32 s100, 1
	s_cbranch_scc1 .Lcv_ret
	s_cmp_eq_u32 s100, 2
	s_cbranch_scc1 .Lp0_rope
	s_mov_b32 s100, 2
	s_sub_i32 s0, s98, 0x400
	s_cmp_lt_u32 s0, 0x140
	s_cbranch_scc0 .Lp0_rope
	s_add_i32 s99, s98, 0x3a00
	s_mov_b32 s101, s99
	s_branch .Lp0_entry
.Lp0_rope:
	s_mov_b32 s14, s97
	v_lshl_or_b32 v2, s93, 9, v0
	s_mov_b32 s0, 0x20000
	v_cmp_gt_i32_e32 vcc, s0, v2
	s_and_saveexec_b64 s[10:11], vcc
	v_readlane_b32 s68, v255, 3
	v_readlane_b32 s69, v255, 4
	s_cbranch_execz .LBB0_220
	s_lshl_b32 s12, s92, 9
	v_ashrrev_i32_e32 v3, 31, v2
	v_lshl_add_u64 v[4:5], v[2:3], 2, s[4:5]
	s_mov_b64 s[0:1], 0x500000
	s_ashr_i32 s13, s12, 31
	s_mov_b32 s20, 0x6dc9c883
	s_mov_b32 s22, 0x54442d18
	v_lshl_add_u64 v[4:5], v[4:5], 0, s[0:1]
	s_lshl_b64 s[16:17], s[12:13], 2
	v_lshl_or_b32 v3, s93, 10, v1
	s_lshl_b32 s13, s92, 10
	s_mov_b64 s[18:19], 0
	v_mov_b32_e32 v8, 0x461c4000
	s_mov_b32 s15, 0x3f2aaaab
	v_mov_b32_e32 v9, 0x3e91f4c4
	s_mov_b32 s26, 0x3f317218
	s_movk_i32 s27, 0x204
	s_mov_b32 s28, 0x7f800000
	s_mov_b32 s29, 0x42b17218
	v_mov_b32_e32 v10, 0x37000000
	s_mov_b32 s30, 0x3fb8aa3b
	s_mov_b32 s31, 0xc2ce8ed0
	v_mov_b32_e32 v11, 0x7f800000
	s_mov_b32 s21, 0x3fc45f30
	s_mov_b32 s23, 0xc01921fb
	s_brev_b32 s33, 18
	s_mov_b32 s34, 0xfe5163ab
	v_mov_b32_e32 v7, 0
	s_mov_b32 s35, 0x3c439041
	s_mov_b32 s36, 0xdb629599
	s_mov_b32 s37, 0xf534ddc0
	s_mov_b32 s38, 0xfc2757d1
	s_mov_b32 s39, 0x4e441529
	s_mov_b32 s40, 0xa2f9836e
	s_mov_b32 s41, 0x3fc90fda
	s_mov_b32 s42, 0x3f22f983
	s_mov_b32 s43, 0xbfc90fda
	v_mov_b32_e32 v12, 0x3c0881c4
	v_mov_b32_e32 v13, 0xbab64f3b
	s_brev_b32 s44, 1
	s_movk_i32 s45, 0x1f8
	s_mov_b32 s46, 0x1ffff
	v_not_b32_e32 v14, 63
	v_not_b32_e32 v15, 31
	v_mov_b32_e32 v16, 0x7fc00000
	s_branch .LBB0_212
